# Mlp1 epilogue: bf16 H stores transposed across lanes (ds_bpermute) into coalesced 64B-per-row pattern, stores pipelined by one group
# speedup vs baseline: 1.0070x; 1.0004x over previous
; #define LAS __attribute__((address_space(3)))
; __device__ __forceinline__ unsigned cvt_pk_bf16(float lo, float hi) { const cvt_f32x2_t v = {lo, hi}; const cvt_bf16x2_t b = __builtin_convertvector(v, cvt_bf16x2_t); return __builtin_bit_cast(unsigned, b); }
; __device__ __forceinline__ void tile_rstd_to_lds(const float* statx, int row0, LAS float* rsl, int wr, int wc, int fr, int fq) {
;     const int t = (wr * 4 + wc) * 64 + fq * 16 + fr;
;     if (t < 256) rsl[t] = row_rstd16(statx, row0 + t);
;     asm volatile("s_waitcnt lgkmcnt(0)" ::: "memory"); __builtin_amdgcn_s_barrier(); asm volatile("" ::: "memory");
;     __device__ __forceinline__ void operator()(const f32x4 (&acc)[2][2][4][2], const Unit& u, int wr, int wc, int fr, int fq) const {
;         const int b = u.pm >> 3, col0 = u.pn * 256 + wc * 32 + 8 * fq;
;         f32x4 sw[2][2];
; #pragma unroll
;         for (int bj = 0; bj < 2; ++bj)
; #pragma unroll
;             for (int n = 0; n < 2; ++n) sw[bj][n] = *(const f32x4*)(shw + (size_t)b * DFF + col0 + 128 * bj + 4 * n);
;         tile_rstd_to_lds(statx, u.pm * 256, rsl, wr, wc, fr, fq);
; #pragma unroll
;         for (int ai = 0; ai < 2; ++ai)
; #pragma unroll
;             for (int m = 0; m < 4; ++m) {
;                 const int row = u.pm * 256 + ai * 128 + wr * 64 + m * 16 + fr;
;                 const float rs = rsl[ai * 128 + wr * 64 + m * 16 + fr];
; #pragma unroll
;                 for (int bj = 0; bj < 2; ++bj) {
;                     f32x4 a = acc[ai][bj][m][0] * rs + sw[bj][0], c = acc[ai][bj][m][1] * rs + sw[bj][1];
; #pragma unroll
;                     for (int e = 0; e < 4; ++e) { a[e] = fmaxf(a[e], 0.f); a[e] *= a[e]; c[e] = fmaxf(c[e], 0.f); c[e] *= c[e]; }
;                     u32x4 w; w.x = cvt_pk_bf16(a[0], a[1]); w.y = cvt_pk_bf16(a[2], a[3]); w.z = cvt_pk_bf16(c[0], c[1]); w.w = cvt_pk_bf16(c[2], c[3]);
;                     *(u32x4*)(H + (size_t)row * DFF + col0 + 128 * bj) = w;
.LBB0_290:
	s_ashr_i32 s44, s81, 3
	s_lshl_b32 s4, s84, 8
	s_ashr_i32 s45, s44, 31
	v_and_b32_e32 v224, 3, v242
	v_lshrrev_b32_e32 v225, 2, v242
	v_lshl_add_u32 v226, v224, 4, v225
	v_lshlrev_b32_e32 v226, 2, v226
	v_sub_u32_e32 v227, v224, v159
	v_lshlrev_b32_e32 v227, 3, v227
	v_sub_u32_e32 v224, v225, v158
	v_mov_b32_e32 v155, v159
	v_mov_b32_e32 v154, v158
	s_or_b32 s4, s4, s64
	s_lshl_b64 s[44:45], s[44:45], 14
	s_add_u32 s44, s59, s44
	v_lshl_add_u32 v156, v155, 3, s4
	s_addc_u32 s45, s62, s45
	v_ashrrev_i32_e32 v157, 31, v156
	v_lshl_add_u64 v[124:125], v[156:157], 2, s[44:45]
	global_load_dwordx4 v[128:131], v[124:125], off offset:16
	global_load_dwordx4 v[132:135], v[124:125], off
	global_load_dwordx4 v[120:123], v[124:125], off offset:528
	s_nop 0
	global_load_dwordx4 v[124:127], v[124:125], off offset:512
	v_lshlrev_b32_e32 v155, 4, v155
	v_add3_u32 v155, s67, v154, v155
	s_movk_i32 s4, 0x100
	s_lshl_b32 s21, s81, 8
	v_cmp_gt_i32_e32 vcc, s4, v155
	s_and_saveexec_b64 s[44:45], vcc
	s_load_dword s85, s[0:1], 0xd8
	s_mov_b32 s90, 0xfffe8000
	s_mov_b32 s91, 0xffff4000
	s_cbranch_execz .LBB0_292
	v_add_u32_e32 v162, s21, v155
	v_ashrrev_i32_e32 v163, 31, v162
	v_lshlrev_b64 v[162:163], 6, v[162:163]
	v_lshl_add_u64 v[174:175], s[6:7], 0, v[162:163]
	global_load_dwordx4 v[162:165], v[174:175], off
	global_load_dwordx4 v[166:169], v[174:175], off offset:32
	global_load_dwordx4 v[170:173], v[174:175], off offset:16
	s_nop 0
	global_load_dwordx4 v[174:177], v[174:175], off offset:48
	v_lshl_add_u32 v155, v155, 2, 0
	v_add_u32_e32 v155, 0x20000, v155
	s_waitcnt vmcnt(0)
	v_mov_b32_e32 v178, v162
	v_mov_b32_e32 v179, v166
	v_mov_b32_e32 v166, v163
	v_mov_b32_e32 v162, v164
	v_mov_b32_e32 v163, v168
	v_mov_b32_e32 v168, v165
	v_mov_b32_e32 v164, v170
	v_mov_b32_e32 v165, v174
	v_mov_b32_e32 v174, v171
	v_mov_b32_e32 v170, v172
	v_mov_b32_e32 v171, v176
	v_mov_b32_e32 v176, v173
	v_pk_add_f32 v[166:167], v[178:179], v[166:167]
	v_pk_add_f32 v[162:163], v[162:163], v[168:169]
	v_pk_add_f32 v[164:165], v[164:165], v[174:175]
	v_pk_add_f32 v[168:169], v[170:171], v[176:177]
	v_pk_add_f32 v[162:163], v[166:167], v[162:163]
	v_pk_add_f32 v[164:165], v[164:165], v[168:169]
	s_nop 0
	v_pk_add_f32 v[162:163], v[162:163], v[164:165]
	s_nop 0
	v_add_f32_e32 v162, v162, v163
	v_fmamk_f32 v162, v162, 0x3a800000, v241
	v_rsq_f32_e32 v162, v162
	ds_write_b32 v155, v162
.LBB0_292:
	s_or_b64 exec, exec, s[44:45]
	v_lshlrev_b32_e32 v163, 2, v154
	s_waitcnt lgkmcnt(0)
	s_barrier
	v_add_u32_e32 v162, s76, v163
	ds_read2_b32 v[164:165], v162 offset1:16
	s_add_i32 s21, s21, s63
	v_add_u32_e32 v154, s21, v154
	v_add_u32_e32 v154, v154, v224
	v_ashrrev_i32_e32 v155, 31, v154
	v_lshlrev_b64 v[166:167], 13, v[154:155]
	s_waitcnt vmcnt(0) lgkmcnt(0)
	v_pk_fma_f32 v[142:143], v[142:143], v[164:165], v[134:135] op_sel_hi:[1,0,1]
	v_pk_fma_f32 v[140:141], v[140:141], v[164:165], v[132:133] op_sel_hi:[1,0,1]
	v_pk_fma_f32 v[136:137], v[136:137], v[164:165], v[128:129] op_sel_hi:[1,0,1]
	v_pk_fma_f32 v[138:139], v[138:139], v[164:165], v[130:131] op_sel_hi:[1,0,1]
	v_max_f32_e32 v140, 0, v140
	v_max_f32_e32 v136, 0, v136
	v_max_f32_e32 v141, 0, v141
	v_max_f32_e32 v137, 0, v137
	v_max_f32_e32 v142, 0, v142
	v_max_f32_e32 v143, 0, v143
	v_pk_mul_f32 v[140:141], v[140:141], v[140:141]
	v_pk_mul_f32 v[136:137], v[136:137], v[136:137]
	v_max_f32_e32 v138, 0, v138
	v_pk_mul_f32 v[142:143], v[142:143], v[142:143]
	v_max_f32_e32 v139, 0, v139
	v_pk_mul_f32 v[168:169], v[138:139], v[138:139]
	v_cvt_pk_bf16_f32 v138, v140, v141
	v_cvt_pk_bf16_f32 v139, v142, v143
	v_cvt_pk_bf16_f32 v140, v136, v137
	v_lshl_add_u64 v[142:143], s[8:9], 0, v[166:167]
	v_add_u32_e32 v156, v156, v227
	v_lshlrev_b64 v[136:137], 1, v[156:157]
	v_pk_fma_f32 v[112:113], v[112:113], v[164:165], v[120:121] op_sel_hi:[1,0,1]
	v_cvt_pk_bf16_f32 v141, v168, v169
	v_lshl_add_u64 v[142:143], v[142:143], 0, v[136:137]
	v_pk_fma_f32 v[118:119], v[118:119], v[164:165], v[126:127] op_sel_hi:[1,0,1]
	v_pk_fma_f32 v[116:117], v[116:117], v[164:165], v[124:125] op_sel_hi:[1,0,1]
	v_pk_fma_f32 v[114:115], v[114:115], v[164:165], v[122:123] op_sel_hi:[1,0,1]
	v_max_f32_e32 v112, 0, v112
	v_max_f32_e32 v113, 0, v113
	ds_bpermute_b32 v228, v226, v138
	ds_bpermute_b32 v229, v226, v139
	ds_bpermute_b32 v230, v226, v140
	ds_bpermute_b32 v231, v226, v141
	v_max_f32_e32 v116, 0, v116
	v_max_f32_e32 v117, 0, v117
	v_pk_mul_f32 v[138:139], v[112:113], v[112:113]
	v_max_f32_e32 v112, 0, v118
	v_max_f32_e32 v114, 0, v114
	v_max_f32_e32 v113, 0, v119
	v_max_f32_e32 v115, 0, v115
	v_pk_mul_f32 v[116:117], v[116:117], v[116:117]
	v_pk_mul_f32 v[118:119], v[112:113], v[112:113]
	v_pk_mul_f32 v[140:141], v[114:115], v[114:115]
	v_cvt_pk_bf16_f32 v112, v116, v117
	v_cvt_pk_bf16_f32 v113, v118, v119
	v_cvt_pk_bf16_f32 v114, v138, v139
	v_cvt_pk_bf16_f32 v115, v140, v141
	s_waitcnt lgkmcnt(0)
; __device__ __forceinline__ unsigned cvt_pk_bf16(float lo, float hi) { const cvt_f32x2_t v = {lo, hi}; const cvt_bf16x2_t b = __builtin_convertvector(v, cvt_bf16x2_t); return __builtin_bit_cast(unsigned, b); }
;     __device__ __forceinline__ void operator()(const f32x4 (&acc)[2][2][4][2], const Unit& u, int wr, int wc, int fr, int fq) const {
;     ...
;         for (int ai = 0; ai < 2; ++ai)
; #pragma unroll
;             for (int m = 0; m < 4; ++m) {
;                 const int row = u.pm * 256 + ai * 128 + wr * 64 + m * 16 + fr;
;                 const float rs = rsl[ai * 128 + wr * 64 + m * 16 + fr];
; #pragma unroll
;                 for (int bj = 0; bj < 2; ++bj) {
;                     f32x4 a = acc[ai][bj][m][0] * rs + sw[bj][0], c = acc[ai][bj][m][1] * rs + sw[bj][1];
; #pragma unroll
;                     for (int e = 0; e < 4; ++e) { a[e] = fmaxf(a[e], 0.f); a[e] *= a[e]; c[e] = fmaxf(c[e], 0.f); c[e] *= c[e]; }
;                     u32x4 w; w.x = cvt_pk_bf16(a[0], a[1]); w.y = cvt_pk_bf16(a[2], a[3]); w.z = cvt_pk_bf16(c[0], c[1]); w.w = cvt_pk_bf16(c[2], c[3]);
;                     *(u32x4*)(H + (size_t)row * DFF + col0 + 128 * bj) = w;
;                 }
	global_store_dwordx4 v[142:143], v[228:231], off
	ds_bpermute_b32 v232, v226, v112
	ds_bpermute_b32 v233, v226, v113
	ds_bpermute_b32 v234, v226, v114
	ds_bpermute_b32 v235, v226, v115
	s_andn2_b64 vcc, exec, s[42:43]
	s_mov_b64 s[42:43], -1
	v_mov_b32_e32 v114, v165
	v_add_u32_e32 v112, 16, v154
	v_pk_fma_f32 v[108:109], v[108:109], v[114:115], v[132:133] op_sel_hi:[1,0,1]
	v_pk_fma_f32 v[104:105], v[104:105], v[114:115], v[128:129] op_sel_hi:[1,0,1]
	v_ashrrev_i32_e32 v113, 31, v112
	v_pk_fma_f32 v[110:111], v[110:111], v[114:115], v[134:135] op_sel_hi:[1,0,1]
	v_pk_fma_f32 v[106:107], v[106:107], v[114:115], v[130:131] op_sel_hi:[1,0,1]
	v_max_f32_e32 v108, 0, v108
	v_max_f32_e32 v104, 0, v104
	v_max_f32_e32 v109, 0, v109
	v_max_f32_e32 v105, 0, v105
	v_lshlrev_b64 v[112:113], 13, v[112:113]
	v_pk_mul_f32 v[108:109], v[108:109], v[108:109]
	v_pk_mul_f32 v[116:117], v[104:105], v[104:105]
	v_max_f32_e32 v104, 0, v110
	v_max_f32_e32 v106, 0, v106
	v_max_f32_e32 v105, 0, v111
	v_max_f32_e32 v107, 0, v107
	v_pk_mul_f32 v[110:111], v[104:105], v[104:105]
	v_pk_mul_f32 v[118:119], v[106:107], v[106:107]
	v_cvt_pk_bf16_f32 v104, v108, v109
	v_lshl_add_u64 v[108:109], s[8:9], 0, v[112:113]
	v_pk_fma_f32 v[100:101], v[100:101], v[114:115], v[124:125] op_sel_hi:[1,0,1]
	v_pk_fma_f32 v[96:97], v[96:97], v[114:115], v[120:121] op_sel_hi:[1,0,1]
	v_cvt_pk_bf16_f32 v105, v110, v111
	v_cvt_pk_bf16_f32 v106, v116, v117
	v_cvt_pk_bf16_f32 v107, v118, v119
	v_lshl_add_u64 v[108:109], v[108:109], 0, v[136:137]
	v_pk_fma_f32 v[102:103], v[102:103], v[114:115], v[126:127] op_sel_hi:[1,0,1]
	v_max_f32_e32 v100, 0, v100
	v_max_f32_e32 v96, 0, v96
	v_max_f32_e32 v101, 0, v101
	v_max_f32_e32 v97, 0, v97
	s_waitcnt lgkmcnt(0)
	global_store_dwordx4 v[142:143], v[232:235], off offset:256
	ds_bpermute_b32 v228, v226, v104
	ds_bpermute_b32 v229, v226, v105
	ds_bpermute_b32 v230, v226, v106
	ds_bpermute_b32 v231, v226, v107
	v_pk_mul_f32 v[100:101], v[100:101], v[100:101]
	v_pk_fma_f32 v[98:99], v[98:99], v[114:115], v[122:123] op_sel_hi:[1,0,1]
	v_pk_mul_f32 v[104:105], v[96:97], v[96:97]
	v_max_f32_e32 v96, 0, v102
	v_max_f32_e32 v97, 0, v103
	v_pk_mul_f32 v[102:103], v[96:97], v[96:97]
	v_cvt_pk_bf16_f32 v96, v100, v101
	ds_read2_b32 v[100:101], v162 offset0:32 offset1:48
	v_max_f32_e32 v98, 0, v98
	v_max_f32_e32 v99, 0, v99
	v_pk_mul_f32 v[106:107], v[98:99], v[98:99]
	v_cvt_pk_bf16_f32 v97, v102, v103
	v_cvt_pk_bf16_f32 v98, v104, v105
	v_cvt_pk_bf16_f32 v99, v106, v107
	s_waitcnt lgkmcnt(0)
	global_store_dwordx4 v[108:109], v[228:231], off
	ds_bpermute_b32 v232, v226, v96
	ds_bpermute_b32 v233, v226, v97
	ds_bpermute_b32 v234, v226, v98
	ds_bpermute_b32 v235, v226, v99
	s_waitcnt lgkmcnt(0)
	v_pk_fma_f32 v[92:93], v[92:93], v[100:101], v[132:133] op_sel_hi:[1,0,1]
	v_pk_fma_f32 v[88:89], v[88:89], v[100:101], v[128:129] op_sel_hi:[1,0,1]
	v_add_u32_e32 v96, 32, v154
	v_ashrrev_i32_e32 v97, 31, v96
	v_pk_fma_f32 v[94:95], v[94:95], v[100:101], v[134:135] op_sel_hi:[1,0,1]
	v_pk_fma_f32 v[90:91], v[90:91], v[100:101], v[130:131] op_sel_hi:[1,0,1]
	v_max_f32_e32 v92, 0, v92
	v_max_f32_e32 v88, 0, v88
	v_max_f32_e32 v93, 0, v93
	v_max_f32_e32 v89, 0, v89
	v_lshlrev_b64 v[96:97], 13, v[96:97]
	v_pk_mul_f32 v[92:93], v[92:93], v[92:93]
	v_pk_mul_f32 v[98:99], v[88:89], v[88:89]
	v_max_f32_e32 v88, 0, v94
	v_max_f32_e32 v90, 0, v90
	v_max_f32_e32 v89, 0, v95
	v_max_f32_e32 v91, 0, v91
	v_pk_mul_f32 v[94:95], v[88:89], v[88:89]
	v_pk_mul_f32 v[102:103], v[90:91], v[90:91]
	v_cvt_pk_bf16_f32 v88, v92, v93
	v_lshl_add_u64 v[92:93], s[8:9], 0, v[96:97]
	v_pk_fma_f32 v[80:81], v[80:81], v[100:101], v[120:121] op_sel_hi:[1,0,1]
	v_cvt_pk_bf16_f32 v89, v94, v95
	v_cvt_pk_bf16_f32 v90, v98, v99
	v_cvt_pk_bf16_f32 v91, v102, v103
	v_lshl_add_u64 v[92:93], v[92:93], 0, v[136:137]
	v_pk_fma_f32 v[86:87], v[86:87], v[100:101], v[126:127] op_sel_hi:[1,0,1]
	v_pk_fma_f32 v[84:85], v[84:85], v[100:101], v[124:125] op_sel_hi:[1,0,1]
	v_pk_fma_f32 v[82:83], v[82:83], v[100:101], v[122:123] op_sel_hi:[1,0,1]
	v_max_f32_e32 v80, 0, v80
	v_max_f32_e32 v81, 0, v81
	s_waitcnt lgkmcnt(0)
	global_store_dwordx4 v[108:109], v[232:235], off offset:256
	ds_bpermute_b32 v228, v226, v88
	ds_bpermute_b32 v229, v226, v89
	ds_bpermute_b32 v230, v226, v90
	ds_bpermute_b32 v231, v226, v91
	v_max_f32_e32 v84, 0, v84
	v_max_f32_e32 v85, 0, v85
	v_pk_mul_f32 v[88:89], v[80:81], v[80:81]
	v_max_f32_e32 v80, 0, v86
	v_max_f32_e32 v82, 0, v82
	v_max_f32_e32 v81, 0, v87
	v_max_f32_e32 v83, 0, v83
	v_pk_mul_f32 v[84:85], v[84:85], v[84:85]
	v_pk_mul_f32 v[86:87], v[80:81], v[80:81]
	v_pk_mul_f32 v[90:91], v[82:83], v[82:83]
	v_cvt_pk_bf16_f32 v80, v84, v85
	v_cvt_pk_bf16_f32 v81, v86, v87
	v_cvt_pk_bf16_f32 v82, v88, v89
	v_cvt_pk_bf16_f32 v83, v90, v91
	s_waitcnt lgkmcnt(0)
	global_store_dwordx4 v[92:93], v[228:231], off
	ds_bpermute_b32 v232, v226, v80
	ds_bpermute_b32 v233, v226, v81
	ds_bpermute_b32 v234, v226, v82
	ds_bpermute_b32 v235, v226, v83
	s_nop 1
	v_mov_b32_e32 v82, v101
	v_add_u32_e32 v80, 48, v154
	v_pk_fma_f32 v[76:77], v[76:77], v[82:83], v[132:133] op_sel_hi:[1,0,1]
	v_pk_fma_f32 v[72:73], v[72:73], v[82:83], v[128:129] op_sel_hi:[1,0,1]
	v_ashrrev_i32_e32 v81, 31, v80
	v_pk_fma_f32 v[78:79], v[78:79], v[82:83], v[134:135] op_sel_hi:[1,0,1]
	v_pk_fma_f32 v[74:75], v[74:75], v[82:83], v[130:131] op_sel_hi:[1,0,1]
	v_max_f32_e32 v76, 0, v76
	v_max_f32_e32 v72, 0, v72
	v_max_f32_e32 v77, 0, v77
	v_max_f32_e32 v73, 0, v73
	v_lshlrev_b64 v[80:81], 13, v[80:81]
	v_pk_mul_f32 v[76:77], v[76:77], v[76:77]
	v_pk_mul_f32 v[84:85], v[72:73], v[72:73]
	v_max_f32_e32 v72, 0, v78
	v_max_f32_e32 v74, 0, v74
	v_max_f32_e32 v73, 0, v79
	v_max_f32_e32 v75, 0, v75
	v_pk_mul_f32 v[78:79], v[72:73], v[72:73]
	v_pk_mul_f32 v[86:87], v[74:75], v[74:75]
	v_cvt_pk_bf16_f32 v72, v76, v77
	v_lshl_add_u64 v[76:77], s[8:9], 0, v[80:81]
	v_pk_fma_f32 v[64:65], v[64:65], v[82:83], v[120:121] op_sel_hi:[1,0,1]
	v_cvt_pk_bf16_f32 v73, v78, v79
	v_cvt_pk_bf16_f32 v74, v84, v85
	v_cvt_pk_bf16_f32 v75, v86, v87
	v_lshl_add_u64 v[76:77], v[76:77], 0, v[136:137]
	v_pk_fma_f32 v[70:71], v[70:71], v[82:83], v[126:127] op_sel_hi:[1,0,1]
	v_pk_fma_f32 v[68:69], v[68:69], v[82:83], v[124:125] op_sel_hi:[1,0,1]
	v_pk_fma_f32 v[66:67], v[66:67], v[82:83], v[122:123] op_sel_hi:[1,0,1]
	v_max_f32_e32 v64, 0, v64
	v_max_f32_e32 v65, 0, v65
	s_waitcnt lgkmcnt(0)
; __device__ __forceinline__ unsigned cvt_pk_bf16(float lo, float hi) { const cvt_f32x2_t v = {lo, hi}; const cvt_bf16x2_t b = __builtin_convertvector(v, cvt_bf16x2_t); return __builtin_bit_cast(unsigned, b); }
;     __device__ __forceinline__ void operator()(const f32x4 (&acc)[2][2][4][2], const Unit& u, int wr, int wc, int fr, int fq) const {
;     ...
;         for (int ai = 0; ai < 2; ++ai)
; #pragma unroll
;             for (int m = 0; m < 4; ++m) {
;                 const int row = u.pm * 256 + ai * 128 + wr * 64 + m * 16 + fr;
;                 const float rs = rsl[ai * 128 + wr * 64 + m * 16 + fr];
; #pragma unroll
;                 for (int bj = 0; bj < 2; ++bj) {
;                     f32x4 a = acc[ai][bj][m][0] * rs + sw[bj][0], c = acc[ai][bj][m][1] * rs + sw[bj][1];
; #pragma unroll
;                     for (int e = 0; e < 4; ++e) { a[e] = fmaxf(a[e], 0.f); a[e] *= a[e]; c[e] = fmaxf(c[e], 0.f); c[e] *= c[e]; }
;                     u32x4 w; w.x = cvt_pk_bf16(a[0], a[1]); w.y = cvt_pk_bf16(a[2], a[3]); w.z = cvt_pk_bf16(c[0], c[1]); w.w = cvt_pk_bf16(c[2], c[3]);
;                     *(u32x4*)(H + (size_t)row * DFF + col0 + 128 * bj) = w;
;                 }
	global_store_dwordx4 v[92:93], v[232:235], off offset:256
	ds_bpermute_b32 v228, v226, v72
	ds_bpermute_b32 v229, v226, v73
	ds_bpermute_b32 v230, v226, v74
	ds_bpermute_b32 v231, v226, v75
	v_max_f32_e32 v68, 0, v68
	v_max_f32_e32 v69, 0, v69
	v_pk_mul_f32 v[72:73], v[64:65], v[64:65]
	v_max_f32_e32 v64, 0, v70
	v_max_f32_e32 v66, 0, v66
	v_max_f32_e32 v65, 0, v71
	v_max_f32_e32 v67, 0, v67
	v_pk_mul_f32 v[68:69], v[68:69], v[68:69]
	v_pk_mul_f32 v[70:71], v[64:65], v[64:65]
	v_pk_mul_f32 v[74:75], v[66:67], v[66:67]
	v_cvt_pk_bf16_f32 v64, v68, v69
	v_cvt_pk_bf16_f32 v65, v70, v71
	v_cvt_pk_bf16_f32 v66, v72, v73
	v_cvt_pk_bf16_f32 v67, v74, v75
	s_waitcnt lgkmcnt(0)
	global_store_dwordx4 v[76:77], v[228:231], off
	ds_bpermute_b32 v232, v226, v64
	ds_bpermute_b32 v233, v226, v65
	ds_bpermute_b32 v234, v226, v66
	ds_bpermute_b32 v235, v226, v67
	ds_read_b32 v68, v162 offset:704
	s_waitcnt lgkmcnt(0)
	v_pk_fma_f32 v[8:9], v[8:9], v[68:69], v[128:129] op_sel_hi:[1,0,1]
	v_add_u32_e32 v64, s77, v163
	ds_read_b32 v64, v64
	v_add_u32_e32 v66, 0x80, v154
	v_ashrrev_i32_e32 v67, 31, v66
	v_lshlrev_b64 v[66:67], 13, v[66:67]
	v_pk_fma_f32 v[16:17], v[16:17], v[68:69], v[132:133] op_sel_hi:[1,0,1]
	s_waitcnt lgkmcnt(0)
	v_pk_fma_f32 v[60:61], v[60:61], v[64:65], v[132:133] op_sel_hi:[1,0,1]
	v_pk_fma_f32 v[56:57], v[56:57], v[64:65], v[128:129] op_sel_hi:[1,0,1]
	v_pk_fma_f32 v[62:63], v[62:63], v[64:65], v[134:135] op_sel_hi:[1,0,1]
	v_pk_fma_f32 v[58:59], v[58:59], v[64:65], v[130:131] op_sel_hi:[1,0,1]
	v_max_f32_e32 v60, 0, v60
	v_max_f32_e32 v56, 0, v56
	v_max_f32_e32 v61, 0, v61
	v_max_f32_e32 v57, 0, v57
	v_pk_mul_f32 v[60:61], v[60:61], v[60:61]
	v_pk_mul_f32 v[70:71], v[56:57], v[56:57]
	v_max_f32_e32 v56, 0, v62
	v_max_f32_e32 v58, 0, v58
	v_max_f32_e32 v57, 0, v63
	v_max_f32_e32 v59, 0, v59
	v_pk_mul_f32 v[62:63], v[56:57], v[56:57]
	v_pk_mul_f32 v[72:73], v[58:59], v[58:59]
	v_cvt_pk_bf16_f32 v56, v60, v61
	v_lshl_add_u64 v[60:61], s[8:9], 0, v[66:67]
	v_pk_fma_f32 v[52:53], v[52:53], v[64:65], v[124:125] op_sel_hi:[1,0,1]
	v_pk_fma_f32 v[44:45], v[44:45], v[64:65], v[120:121] op_sel_hi:[1,0,1]
	v_cvt_pk_bf16_f32 v57, v62, v63
	v_cvt_pk_bf16_f32 v58, v70, v71
	v_cvt_pk_bf16_f32 v59, v72, v73
	v_lshl_add_u64 v[60:61], v[60:61], 0, v[136:137]
	v_pk_fma_f32 v[54:55], v[54:55], v[64:65], v[126:127] op_sel_hi:[1,0,1]
	v_max_f32_e32 v52, 0, v52
	v_max_f32_e32 v44, 0, v44
	v_max_f32_e32 v53, 0, v53
	v_max_f32_e32 v45, 0, v45
	s_waitcnt lgkmcnt(0)
	global_store_dwordx4 v[76:77], v[232:235], off offset:256
	ds_bpermute_b32 v228, v226, v56
	ds_bpermute_b32 v229, v226, v57
	ds_bpermute_b32 v230, v226, v58
	ds_bpermute_b32 v231, v226, v59
	v_pk_mul_f32 v[52:53], v[52:53], v[52:53]
	v_pk_fma_f32 v[46:47], v[46:47], v[64:65], v[122:123] op_sel_hi:[1,0,1]
	v_pk_mul_f32 v[56:57], v[44:45], v[44:45]
	v_max_f32_e32 v44, 0, v54
	v_max_f32_e32 v45, 0, v55
	v_pk_mul_f32 v[54:55], v[44:45], v[44:45]
	v_cvt_pk_bf16_f32 v44, v52, v53
	ds_read2_b32 v[52:53], v162 offset0:144 offset1:160
	v_max_f32_e32 v46, 0, v46
	v_max_f32_e32 v47, 0, v47
	v_pk_mul_f32 v[58:59], v[46:47], v[46:47]
	v_cvt_pk_bf16_f32 v45, v54, v55
	v_cvt_pk_bf16_f32 v46, v56, v57
	v_cvt_pk_bf16_f32 v47, v58, v59
	s_waitcnt lgkmcnt(0)
	global_store_dwordx4 v[60:61], v[228:231], off
	ds_bpermute_b32 v232, v226, v44
	ds_bpermute_b32 v233, v226, v45
	ds_bpermute_b32 v234, v226, v46
	ds_bpermute_b32 v235, v226, v47
	s_waitcnt lgkmcnt(0)
	v_pk_fma_f32 v[40:41], v[40:41], v[52:53], v[128:129] op_sel_hi:[1,0,1]
	v_pk_fma_f32 v[48:49], v[48:49], v[52:53], v[132:133] op_sel_hi:[1,0,1]
	v_add_u32_e32 v44, 0x90, v154
	v_ashrrev_i32_e32 v45, 31, v44
	v_pk_fma_f32 v[46:47], v[50:51], v[52:53], v[134:135] op_sel_hi:[1,0,1]
	v_pk_fma_f32 v[42:43], v[42:43], v[52:53], v[130:131] op_sel_hi:[1,0,1]
	v_max_f32_e32 v40, 0, v40
	v_max_f32_e32 v41, 0, v41
	v_lshlrev_b64 v[44:45], 13, v[44:45]
	v_max_f32_e32 v48, 0, v48
	v_max_f32_e32 v49, 0, v49
	v_pk_mul_f32 v[50:51], v[40:41], v[40:41]
	v_max_f32_e32 v40, 0, v46
	v_max_f32_e32 v42, 0, v42
	v_max_f32_e32 v41, 0, v47
	v_max_f32_e32 v43, 0, v43
	v_pk_mul_f32 v[48:49], v[48:49], v[48:49]
	v_pk_mul_f32 v[46:47], v[40:41], v[40:41]
	v_pk_mul_f32 v[54:55], v[42:43], v[42:43]
	v_lshl_add_u64 v[44:45], s[8:9], 0, v[44:45]
	v_pk_fma_f32 v[28:29], v[28:29], v[52:53], v[120:121] op_sel_hi:[1,0,1]
	v_cvt_pk_bf16_f32 v40, v48, v49
	v_cvt_pk_bf16_f32 v41, v46, v47
	v_cvt_pk_bf16_f32 v42, v50, v51
	v_cvt_pk_bf16_f32 v43, v54, v55
	v_lshl_add_u64 v[44:45], v[44:45], 0, v[136:137]
	v_pk_fma_f32 v[38:39], v[38:39], v[52:53], v[126:127] op_sel_hi:[1,0,1]
	v_pk_fma_f32 v[36:37], v[36:37], v[52:53], v[124:125] op_sel_hi:[1,0,1]
	v_pk_fma_f32 v[30:31], v[30:31], v[52:53], v[122:123] op_sel_hi:[1,0,1]
	v_max_f32_e32 v28, 0, v28
	v_max_f32_e32 v29, 0, v29
	s_waitcnt lgkmcnt(0)
; __device__ __forceinline__ unsigned cvt_pk_bf16(float lo, float hi) { const cvt_f32x2_t v = {lo, hi}; const cvt_bf16x2_t b = __builtin_convertvector(v, cvt_bf16x2_t); return __builtin_bit_cast(unsigned, b); }
;     __device__ __forceinline__ void operator()(const f32x4 (&acc)[2][2][4][2], const Unit& u, int wr, int wc, int fr, int fq) const {
;     ...
;         for (int ai = 0; ai < 2; ++ai)
; #pragma unroll
;             for (int m = 0; m < 4; ++m) {
;                 const int row = u.pm * 256 + ai * 128 + wr * 64 + m * 16 + fr;
;                 const float rs = rsl[ai * 128 + wr * 64 + m * 16 + fr];
; #pragma unroll
;                 for (int bj = 0; bj < 2; ++bj) {
;                     f32x4 a = acc[ai][bj][m][0] * rs + sw[bj][0], c = acc[ai][bj][m][1] * rs + sw[bj][1];
; #pragma unroll
;                     for (int e = 0; e < 4; ++e) { a[e] = fmaxf(a[e], 0.f); a[e] *= a[e]; c[e] = fmaxf(c[e], 0.f); c[e] *= c[e]; }
;                     u32x4 w; w.x = cvt_pk_bf16(a[0], a[1]); w.y = cvt_pk_bf16(a[2], a[3]); w.z = cvt_pk_bf16(c[0], c[1]); w.w = cvt_pk_bf16(c[2], c[3]);
;                     *(u32x4*)(H + (size_t)row * DFF + col0 + 128 * bj) = w;
;                 }
	global_store_dwordx4 v[60:61], v[232:235], off offset:256
	ds_bpermute_b32 v228, v226, v40
	ds_bpermute_b32 v229, v226, v41
	ds_bpermute_b32 v230, v226, v42
	ds_bpermute_b32 v231, v226, v43
	v_max_f32_e32 v36, 0, v36
	v_max_f32_e32 v37, 0, v37
	v_pk_mul_f32 v[40:41], v[28:29], v[28:29]
	v_max_f32_e32 v28, 0, v38
	v_max_f32_e32 v30, 0, v30
	v_max_f32_e32 v29, 0, v39
	v_max_f32_e32 v31, 0, v31
	v_pk_mul_f32 v[36:37], v[36:37], v[36:37]
	v_pk_mul_f32 v[38:39], v[28:29], v[28:29]
	v_pk_mul_f32 v[42:43], v[30:31], v[30:31]
	v_cvt_pk_bf16_f32 v28, v36, v37
	v_cvt_pk_bf16_f32 v29, v38, v39
	v_cvt_pk_bf16_f32 v30, v40, v41
	v_cvt_pk_bf16_f32 v31, v42, v43
	s_waitcnt lgkmcnt(0)
	global_store_dwordx4 v[44:45], v[228:231], off
	ds_bpermute_b32 v232, v226, v28
	ds_bpermute_b32 v233, v226, v29
	ds_bpermute_b32 v234, v226, v30
	ds_bpermute_b32 v235, v226, v31
	v_pk_fma_f32 v[10:11], v[10:11], v[68:69], v[130:131] op_sel_hi:[1,0,1]
	v_max_f32_e32 v8, 0, v8
	v_mov_b32_e32 v30, v53
	v_add_u32_e32 v28, 0xa0, v154
	v_pk_fma_f32 v[24:25], v[24:25], v[30:31], v[128:129] op_sel_hi:[1,0,1]
	v_ashrrev_i32_e32 v29, 31, v28
	v_pk_fma_f32 v[34:35], v[34:35], v[30:31], v[134:135] op_sel_hi:[1,0,1]
	v_pk_fma_f32 v[32:33], v[32:33], v[30:31], v[132:133] op_sel_hi:[1,0,1]
	v_pk_fma_f32 v[26:27], v[26:27], v[30:31], v[130:131] op_sel_hi:[1,0,1]
	v_max_f32_e32 v24, 0, v24
	v_max_f32_e32 v25, 0, v25
	v_lshlrev_b64 v[28:29], 13, v[28:29]
	v_max_f32_e32 v32, 0, v32
	v_max_f32_e32 v33, 0, v33
	v_pk_mul_f32 v[36:37], v[24:25], v[24:25]
	v_max_f32_e32 v24, 0, v34
	v_max_f32_e32 v26, 0, v26
	v_max_f32_e32 v25, 0, v35
	v_max_f32_e32 v27, 0, v27
	v_pk_mul_f32 v[32:33], v[32:33], v[32:33]
	v_pk_mul_f32 v[34:35], v[24:25], v[24:25]
	v_pk_mul_f32 v[38:39], v[26:27], v[26:27]
	v_lshl_add_u64 v[28:29], s[8:9], 0, v[28:29]
	v_pk_fma_f32 v[12:13], v[12:13], v[30:31], v[120:121] op_sel_hi:[1,0,1]
	v_cvt_pk_bf16_f32 v24, v32, v33
	v_cvt_pk_bf16_f32 v25, v34, v35
	v_cvt_pk_bf16_f32 v26, v36, v37
	v_cvt_pk_bf16_f32 v27, v38, v39
	v_lshl_add_u64 v[28:29], v[28:29], 0, v[136:137]
	v_pk_fma_f32 v[22:23], v[22:23], v[30:31], v[126:127] op_sel_hi:[1,0,1]
	v_pk_fma_f32 v[20:21], v[20:21], v[30:31], v[124:125] op_sel_hi:[1,0,1]
	v_pk_fma_f32 v[14:15], v[14:15], v[30:31], v[122:123] op_sel_hi:[1,0,1]
	v_max_f32_e32 v12, 0, v12
	v_max_f32_e32 v13, 0, v13
	s_waitcnt lgkmcnt(0)
	global_store_dwordx4 v[44:45], v[232:235], off offset:256
	ds_bpermute_b32 v228, v226, v24
	ds_bpermute_b32 v229, v226, v25
	ds_bpermute_b32 v230, v226, v26
	ds_bpermute_b32 v231, v226, v27
	v_max_f32_e32 v20, 0, v20
	v_max_f32_e32 v21, 0, v21
	v_pk_mul_f32 v[24:25], v[12:13], v[12:13]
	v_max_f32_e32 v12, 0, v22
	v_max_f32_e32 v14, 0, v14
	v_max_f32_e32 v13, 0, v23
	v_max_f32_e32 v15, 0, v15
	v_pk_mul_f32 v[20:21], v[20:21], v[20:21]
	v_pk_mul_f32 v[22:23], v[12:13], v[12:13]
	v_pk_mul_f32 v[26:27], v[14:15], v[14:15]
	v_cvt_pk_bf16_f32 v12, v20, v21
	v_cvt_pk_bf16_f32 v13, v22, v23
	v_cvt_pk_bf16_f32 v14, v24, v25
	v_cvt_pk_bf16_f32 v15, v26, v27
	s_waitcnt lgkmcnt(0)
	global_store_dwordx4 v[28:29], v[228:231], off
	ds_bpermute_b32 v232, v226, v12
	ds_bpermute_b32 v233, v226, v13
	ds_bpermute_b32 v234, v226, v14
	ds_bpermute_b32 v235, v226, v15
	v_max_f32_e32 v9, 0, v9
	v_max_f32_e32 v16, 0, v16
	v_add_u32_e32 v12, 0xb0, v154
	v_ashrrev_i32_e32 v13, 31, v12
	v_pk_fma_f32 v[14:15], v[18:19], v[68:69], v[134:135] op_sel_hi:[1,0,1]
	v_lshlrev_b64 v[12:13], 13, v[12:13]
	v_max_f32_e32 v17, 0, v17
	v_pk_mul_f32 v[18:19], v[8:9], v[8:9]
	v_max_f32_e32 v8, 0, v14
	v_max_f32_e32 v10, 0, v10
	v_max_f32_e32 v9, 0, v15
	v_max_f32_e32 v11, 0, v11
	v_pk_mul_f32 v[16:17], v[16:17], v[16:17]
	v_pk_mul_f32 v[14:15], v[8:9], v[8:9]
	v_pk_mul_f32 v[20:21], v[10:11], v[10:11]
	v_lshl_add_u64 v[12:13], s[8:9], 0, v[12:13]
	v_pk_fma_f32 v[0:1], v[0:1], v[68:69], v[120:121] op_sel_hi:[1,0,1]
	v_cvt_pk_bf16_f32 v8, v16, v17
	v_cvt_pk_bf16_f32 v9, v14, v15
	v_cvt_pk_bf16_f32 v10, v18, v19
	v_cvt_pk_bf16_f32 v11, v20, v21
	v_lshl_add_u64 v[12:13], v[12:13], 0, v[136:137]
	v_pk_fma_f32 v[6:7], v[6:7], v[68:69], v[126:127] op_sel_hi:[1,0,1]
	v_pk_fma_f32 v[4:5], v[4:5], v[68:69], v[124:125] op_sel_hi:[1,0,1]
	v_pk_fma_f32 v[2:3], v[2:3], v[68:69], v[122:123] op_sel_hi:[1,0,1]
	v_max_f32_e32 v0, 0, v0
	v_max_f32_e32 v1, 0, v1
	s_waitcnt lgkmcnt(0)
	global_store_dwordx4 v[28:29], v[232:235], off offset:256
	ds_bpermute_b32 v228, v226, v8
	ds_bpermute_b32 v229, v226, v9
	ds_bpermute_b32 v230, v226, v10
	ds_bpermute_b32 v231, v226, v11
	v_max_f32_e32 v4, 0, v4
	v_max_f32_e32 v5, 0, v5
	v_pk_mul_f32 v[8:9], v[0:1], v[0:1]
	v_max_f32_e32 v0, 0, v6
	v_max_f32_e32 v2, 0, v2
	v_max_f32_e32 v1, 0, v7
	v_max_f32_e32 v3, 0, v3
	v_pk_mul_f32 v[4:5], v[4:5], v[4:5]
	v_pk_mul_f32 v[6:7], v[0:1], v[0:1]
	v_pk_mul_f32 v[10:11], v[2:3], v[2:3]
	v_cvt_pk_bf16_f32 v0, v4, v5
	v_cvt_pk_bf16_f32 v1, v6, v7
	v_cvt_pk_bf16_f32 v2, v8, v9
	v_cvt_pk_bf16_f32 v3, v10, v11
	s_waitcnt lgkmcnt(0)
	global_store_dwordx4 v[12:13], v[228:231], off
	ds_bpermute_b32 v232, v226, v0
	ds_bpermute_b32 v233, v226, v1
	ds_bpermute_b32 v234, v226, v2
	ds_bpermute_b32 v235, v226, v3
	s_waitcnt lgkmcnt(0)
	global_store_dwordx4 v[12:13], v[232:235], off offset:256
	s_cbranch_vccnz .LBB0_279
	v_readlane_b32 s4, v255, 46
	v_readlane_b32 s5, v255, 47
	s_andn2_b64 vcc, exec, s[4:5]
	s_cbranch_vccnz .LBB0_278
	s_barrier
	s_branch .LBB0_278
